# GEMM K-loops: first iteration peeled with MFMA SrcC=0, accumulator zeroing (128 v_mov per unit) removed
# speedup vs baseline: 1.0153x; 1.0099x over previous
; #define PG8_STAGE(bufoff, gbase, voff) do { _Pragma("unroll") for (int _i = 0; _i < 2; ++_i) \
;         __builtin_amdgcn_global_load_lds((const unsigned*)((const char*)(gbase) + (voff)[_i]), (PG8_LAS unsigned*)(lds + (bufoff) + ldsw + _i * 8192), 16, 0, 0); } while (0)
; #define PG8_LDA(dst, b, h) do { _Pragma("unroll") for (int m = 0; m < 4; ++m) _Pragma("unroll") for (int k = 0; k < 2; ++k) dst[m][k] = *(const PG8_LAS bf16x8*)(lds + PG8_SA(b, h) + aoff + m * 2048 + k * 1024); } while (0)
; #define PG8_LDB(dst, b, h) do { _Pragma("unroll") for (int n = 0; n < 2; ++n) _Pragma("unroll") for (int k = 0; k < 2; ++k) dst[n][k] = *(const PG8_LAS bf16x8*)(lds + PG8_SB(b, h) + boff + n * 2048 + k * 1024); } while (0)
; #define PG8_WAIT_V(n) asm volatile("s_waitcnt vmcnt(" #n ")" ::: "memory")
; #define PG8_WAIT_L(n) asm volatile("s_waitcnt lgkmcnt(" #n ")" ::: "memory")
; #define PG8_BAR __builtin_amdgcn_s_barrier()
; template <class Epi, class Sched, bool ALIGN_EPI = false, bool SP2 = false>
; __device__ __forceinline__ void gemm_phase(PG8_LAS unsigned char* lds, const Gemm g, const Sched& S, const Epi& E) {
;     ...
;         const bool has_next = S.next(ui + 1, nxt);
;         const char* nA = has_next ? (const char*)g.A + (size_t)nxt.pm * tstep + (size_t)nxt.kt0 * kstep : cA; const char* nB = has_next ? (const char*)g.Bt + (size_t)nxt.pn * tstep + (size_t)nxt.kt0 * kstep : cB;
;         const int nt = cur.nt;
;         for (int t = 0; t < nt; t += 2) {
;             const bool last = (t == nt - 2);
;             const char* a1 = cA + (size_t)(t + 1) * kstep;
;             const char* a2 = last ? nA : cA + (size_t)(t + 2) * kstep; const char* b2 = last ? nB : cB + (size_t)(t + 2) * kstep;
;             const char* a3 = a2 + kstep; const char* b3 = b2 + kstep;
;             if (last && has_next) S.a_ready(nxt);
;             if constexpr (SP2) {
;             PG8_LDB(B0, 0, 0); PG8_LDB(B1, 0, 1); PG8_SCHED; PG8_LDA(At, 0, 0); PG8_STAGE(PG8_SA(1, 1), a1 + hstep, voffA);
;             PG8_WAIT_V(8); PG8_WAIT_L(0); PG8_BAR; PG8_MMA(0, 0, At, B0); PG8_MMA(0, 1, At, B1); PG8_BAR; PG8_SCHED;
;             PG8_LDA(At, 0, 1); PG8_STAGE(PG8_SB(0, 0), b2, voffB); PG8_STAGE(PG8_SB(0, 1), b2 + hstep, voffB); PG8_STAGE(PG8_SA(0, 0), a2, voffA);
;             PG8_WAIT_V(8); PG8_WAIT_L(0); PG8_BAR; PG8_MMA(1, 0, At, B0); PG8_MMA(1, 1, At, B1); PG8_BAR; PG8_SCHED;
.LBB0_235:
	s_ashr_i32 s41, s40, 31
	s_lshl_b64 s[42:43], s[40:41], 19
	s_add_u32 s42, s22, s42
	s_addc_u32 s43, s23, s43
	s_and_b64 s[44:45], s[36:37], exec
	s_cselect_b32 s66, s43, s87
	s_cselect_b32 s67, s42, s86
	s_ashr_i32 s39, s38, 31
	s_lshl_b64 s[44:45], s[38:39], 19
	s_add_u32 s44, s11, s44
	s_addc_u32 s45, s12, s45
	s_and_b64 s[68:69], s[36:37], exec
	s_cselect_b32 s39, s45, s89
	s_cselect_b32 s68, s44, s88
	s_add_u32 s86, s86, 0x40080
	s_addc_u32 s87, s87, 0
	s_add_u32 s69, s88, 0x100
	s_addc_u32 s71, s89, 0
	s_mov_b32 s75, -2
	s_waitcnt vmcnt(0)
	s_add_u32 s76, s86, 0xfffc0080
	s_addc_u32 s77, s87, -1
	s_add_i32 s80, 0, 0x10000
	s_cmp_eq_u32 s75, 12
	s_cselect_b32 s91, s66, s77
	s_cselect_b32 s90, s67, s76
	s_cselect_b32 s89, s39, s71
	s_cselect_b32 s88, s68, s69
	s_add_i32 s81, 0, 0x14000
	v_add_u32_e32 v154, s80, v176
	v_add_u32_e32 v186, s81, v176
	ds_read_b128 v[48:51], v154
	ds_read_b128 v[60:63], v154 offset:1024
	ds_read_b128 v[138:141], v154 offset:2048
	ds_read_b128 v[154:157], v154 offset:3072
	ds_read_b128 v[158:161], v186
	ds_read_b128 v[178:181], v186 offset:1024
	ds_read_b128 v[182:185], v186 offset:2048
	ds_read_b128 v[186:189], v186 offset:3072
	v_lshl_add_u64 v[194:195], s[86:87], 0, v[150:151]
	s_add_i32 m0, s15, 0xc000
	ds_read_b128 v[190:193], v177
	ds_read_b128 v[212:215], v177 offset:1024
	ds_read_b128 v[216:219], v177 offset:2048
	ds_read_b128 v[220:223], v177 offset:3072
	ds_read_b128 v[224:227], v177 offset:4096
	ds_read_b128 v[228:231], v177 offset:5120
	ds_read_b128 v[232:235], v177 offset:6144
	ds_read_b128 v[236:239], v177 offset:7168
	global_load_lds_dwordx4 v[194:195], off
	v_lshl_add_u64 v[194:195], s[86:87], 0, v[152:153]
	s_add_i32 m0, s15, 0xe000
	s_nop 0
	global_load_lds_dwordx4 v[194:195], off
	s_waitcnt vmcnt(8)
	s_waitcnt lgkmcnt(0)
	s_barrier
	s_setprio 1
	s_waitcnt lgkmcnt(0)
	v_mfma_f32_16x16x32_bf16 v[134:137], v[48:51], v[190:193], 0
	v_mfma_f32_16x16x32_bf16 v[126:129], v[138:141], v[190:193], 0
	v_mfma_f32_16x16x32_bf16 v[110:113], v[138:141], v[216:219], 0
	v_mfma_f32_16x16x32_bf16 v[118:121], v[48:51], v[216:219], 0
	v_mfma_f32_16x16x32_bf16 v[102:105], v[48:51], v[224:227], 0
	v_mfma_f32_16x16x32_bf16 v[94:97], v[138:141], v[224:227], 0
	v_mfma_f32_16x16x32_bf16 v[76:79], v[138:141], v[232:235], 0
	v_mfma_f32_16x16x32_bf16 v[86:89], v[48:51], v[232:235], 0
	v_mfma_f32_16x16x32_bf16 v[134:137], v[60:63], v[212:215], v[134:137]
	v_mfma_f32_16x16x32_bf16 v[126:129], v[154:157], v[212:215], v[126:129]
	v_mfma_f32_16x16x32_bf16 v[110:113], v[154:157], v[220:223], v[110:113]
	v_mfma_f32_16x16x32_bf16 v[118:121], v[60:63], v[220:223], v[118:121]
	v_mfma_f32_16x16x32_bf16 v[102:105], v[60:63], v[228:231], v[102:105]
	v_mfma_f32_16x16x32_bf16 v[94:97], v[154:157], v[228:231], v[94:97]
	v_mfma_f32_16x16x32_bf16 v[76:79], v[154:157], v[236:239], v[76:79]
	v_mfma_f32_16x16x32_bf16 v[86:89], v[60:63], v[236:239], v[86:89]
	v_mfma_f32_16x16x32_bf16 v[130:133], v[158:161], v[190:193], 0
	v_mfma_f32_16x16x32_bf16 v[122:125], v[182:185], v[190:193], 0
	v_mfma_f32_16x16x32_bf16 v[106:109], v[182:185], v[216:219], 0
	v_mfma_f32_16x16x32_bf16 v[114:117], v[158:161], v[216:219], 0
	v_mfma_f32_16x16x32_bf16 v[98:101], v[158:161], v[224:227], 0
	v_mfma_f32_16x16x32_bf16 v[90:93], v[182:185], v[224:227], 0
	v_mfma_f32_16x16x32_bf16 v[72:75], v[182:185], v[232:235], 0
	v_mfma_f32_16x16x32_bf16 v[82:85], v[158:161], v[232:235], 0
	v_mfma_f32_16x16x32_bf16 v[130:133], v[178:181], v[212:215], v[130:133]
	v_mfma_f32_16x16x32_bf16 v[122:125], v[186:189], v[212:215], v[122:125]
	v_mfma_f32_16x16x32_bf16 v[106:109], v[186:189], v[220:223], v[106:109]
	v_mfma_f32_16x16x32_bf16 v[114:117], v[178:181], v[220:223], v[114:117]
	v_mfma_f32_16x16x32_bf16 v[98:101], v[178:181], v[228:231], v[98:101]
	v_mfma_f32_16x16x32_bf16 v[90:93], v[186:189], v[228:231], v[90:93]
	v_mfma_f32_16x16x32_bf16 v[72:75], v[186:189], v[236:239], v[72:75]
	v_mfma_f32_16x16x32_bf16 v[82:85], v[178:181], v[236:239], v[82:85]
	s_setprio 0
	s_barrier
	s_add_i32 s76, s80, s13
	v_lshl_add_u64 v[194:195], s[88:89], 0, v[144:145]
	s_mov_b32 m0, s76
	ds_read_b128 v[190:193], v177 offset:16384
	ds_read_b128 v[212:215], v177 offset:17408
	ds_read_b128 v[216:219], v177 offset:18432
	ds_read_b128 v[220:223], v177 offset:19456
	ds_read_b128 v[224:227], v177 offset:20480
	ds_read_b128 v[228:231], v177 offset:21504
	ds_read_b128 v[232:235], v177 offset:22528
	ds_read_b128 v[236:239], v177 offset:23552
	global_load_lds_dwordx4 v[194:195], off
	s_add_i32 m0, s76, 0x2000
	s_add_u32 s76, s88, 0x40000
	v_lshl_add_u64 v[240:241], s[88:89], 0, v[148:149]
	s_addc_u32 s77, s89, 0
	s_add_i32 s80, s81, s13
	global_load_lds_dwordx4 v[240:241], off
	v_lshl_add_u64 v[242:243], s[76:77], 0, v[144:145]
	s_mov_b32 m0, s80
	v_lshl_add_u64 v[244:245], s[90:91], 0, v[146:147]
	global_load_lds_dwordx4 v[242:243], off
	v_lshl_add_u64 v[242:243], s[76:77], 0, v[148:149]
	s_add_i32 m0, s80, 0x2000
	s_nop 0
	global_load_lds_dwordx4 v[242:243], off
	v_lshl_add_u64 v[242:243], s[90:91], 0, v[142:143]
	s_mov_b32 m0, s15
	s_nop 0
	global_load_lds_dwordx4 v[242:243], off
	s_mov_b32 m0, s16
	s_nop 0
	global_load_lds_dwordx4 v[244:245], off
	s_waitcnt vmcnt(8)
	s_waitcnt lgkmcnt(0)
	s_barrier
; #define PG8_STAGE(bufoff, gbase, voff) do { _Pragma("unroll") for (int _i = 0; _i < 2; ++_i) \
;         __builtin_amdgcn_global_load_lds((const unsigned*)((const char*)(gbase) + (voff)[_i]), (PG8_LAS unsigned*)(lds + (bufoff) + ldsw + _i * 8192), 16, 0, 0); } while (0)
; #define PG8_LDA(dst, b, h) do { _Pragma("unroll") for (int m = 0; m < 4; ++m) _Pragma("unroll") for (int k = 0; k < 2; ++k) dst[m][k] = *(const PG8_LAS bf16x8*)(lds + PG8_SA(b, h) + aoff + m * 2048 + k * 1024); } while (0)
; #define PG8_LDB(dst, b, h) do { _Pragma("unroll") for (int n = 0; n < 2; ++n) _Pragma("unroll") for (int k = 0; k < 2; ++k) dst[n][k] = *(const PG8_LAS bf16x8*)(lds + PG8_SB(b, h) + boff + n * 2048 + k * 1024); } while (0)
; #define PG8_MMA(ai, bj, At, Bt) do { __builtin_amdgcn_s_setprio(1); _Pragma("unroll") for (int m = 0; m < 4; ++m) _Pragma("unroll") for (int n = 0; n < 2; ++n) _Pragma("unroll") for (int k = 0; k < 2; ++k) \
;         acc[ai][bj][m][n] = __builtin_amdgcn_mfma_f32_16x16x32_bf16(Bt[n][k], At[m][k], acc[ai][bj][m][n], 0, 0, 0); __builtin_amdgcn_s_setprio(0); } while (0)
; #define PG8_WAIT_V(n) asm volatile("s_waitcnt vmcnt(" #n ")" ::: "memory")
; #define PG8_WAIT_L(n) asm volatile("s_waitcnt lgkmcnt(" #n ")" ::: "memory")
; #define PG8_BAR __builtin_amdgcn_s_barrier()
; #define PG8_SCHED __builtin_amdgcn_sched_barrier(0)
; template <class Epi, class Sched, bool ALIGN_EPI = false, bool SP2 = false>
; __device__ __forceinline__ void gemm_phase(PG8_LAS unsigned char* lds, const Gemm g, const Sched& S, const Epi& E) {
;     ...
;             PG8_WAIT_V(8); PG8_WAIT_L(0); PG8_BAR; PG8_MMA(1, 0, At, B0); PG8_MMA(1, 1, At, B1); PG8_BAR; PG8_SCHED;
;             PG8_LDB(B0, 1, 0); PG8_LDB(B1, 1, 1); PG8_SCHED; PG8_LDA(At, 1, 0); PG8_STAGE(PG8_SA(0, 1), a2 + hstep, voffA);
;             PG8_WAIT_V(8); PG8_WAIT_L(0); PG8_BAR; PG8_MMA(0, 0, At, B0); PG8_MMA(0, 1, At, B1); PG8_BAR; PG8_SCHED;
	s_setprio 1
	s_waitcnt lgkmcnt(0)
	v_mfma_f32_16x16x32_bf16 v[68:71], v[48:51], v[190:193], 0
	v_mfma_f32_16x16x32_bf16 v[56:59], v[138:141], v[190:193], 0
	v_mfma_f32_16x16x32_bf16 v[36:39], v[138:141], v[216:219], 0
	v_mfma_f32_16x16x32_bf16 v[44:47], v[48:51], v[216:219], 0
	v_mfma_f32_16x16x32_bf16 v[28:31], v[48:51], v[224:227], 0
	v_mfma_f32_16x16x32_bf16 v[20:23], v[138:141], v[224:227], 0
	v_mfma_f32_16x16x32_bf16 v[4:7], v[138:141], v[232:235], 0
	v_mfma_f32_16x16x32_bf16 v[12:15], v[48:51], v[232:235], 0
	v_mfma_f32_16x16x32_bf16 v[68:71], v[60:63], v[212:215], v[68:71]
	v_mfma_f32_16x16x32_bf16 v[56:59], v[154:157], v[212:215], v[56:59]
	v_mfma_f32_16x16x32_bf16 v[36:39], v[154:157], v[220:223], v[36:39]
	v_mfma_f32_16x16x32_bf16 v[44:47], v[60:63], v[220:223], v[44:47]
	v_mfma_f32_16x16x32_bf16 v[28:31], v[60:63], v[228:231], v[28:31]
	v_mfma_f32_16x16x32_bf16 v[20:23], v[154:157], v[228:231], v[20:23]
	v_mfma_f32_16x16x32_bf16 v[4:7], v[154:157], v[236:239], v[4:7]
	v_mfma_f32_16x16x32_bf16 v[12:15], v[60:63], v[236:239], v[12:15]
	v_mfma_f32_16x16x32_bf16 v[52:55], v[182:185], v[190:193], 0
	v_mfma_f32_16x16x32_bf16 v[40:43], v[158:161], v[216:219], 0
	v_mfma_f32_16x16x32_bf16 v[32:35], v[182:185], v[216:219], 0
	v_mfma_f32_16x16x32_bf16 v[24:27], v[158:161], v[224:227], 0
	v_mfma_f32_16x16x32_bf16 v[16:19], v[182:185], v[224:227], 0
	v_mfma_f32_16x16x32_bf16 v[8:11], v[158:161], v[232:235], 0
	v_mfma_f32_16x16x32_bf16 v[0:3], v[182:185], v[232:235], 0
	v_mfma_f32_16x16x32_bf16 v[48:51], v[158:161], v[190:193], 0
	v_mfma_f32_16x16x32_bf16 v[52:55], v[186:189], v[212:215], v[52:55]
	v_mfma_f32_16x16x32_bf16 v[40:43], v[178:181], v[220:223], v[40:43]
	v_mfma_f32_16x16x32_bf16 v[32:35], v[186:189], v[220:223], v[32:35]
	v_mfma_f32_16x16x32_bf16 v[24:27], v[178:181], v[228:231], v[24:27]
	v_mfma_f32_16x16x32_bf16 v[16:19], v[186:189], v[228:231], v[16:19]
	v_mfma_f32_16x16x32_bf16 v[8:11], v[178:181], v[236:239], v[8:11]
	v_mfma_f32_16x16x32_bf16 v[0:3], v[186:189], v[236:239], v[0:3]
	v_mfma_f32_16x16x32_bf16 v[48:51], v[178:181], v[212:215], v[48:51]
	s_setprio 0
	s_barrier
	s_add_i32 s80, 0, 0x18000
	s_add_i32 s81, 0, 0x1c000
	v_add_u32_e32 v154, s80, v176
	v_add_u32_e32 v186, s81, v176
	ds_read_b128 v[60:63], v154
	ds_read_b128 v[64:67], v154 offset:1024
	ds_read_b128 v[138:141], v154 offset:2048
	ds_read_b128 v[154:157], v154 offset:3072
	ds_read_b128 v[158:161], v186
	ds_read_b128 v[178:181], v186 offset:1024
	ds_read_b128 v[182:185], v186 offset:2048
	ds_read_b128 v[186:189], v186 offset:3072
	s_add_u32 s76, s90, 0x40000
	s_addc_u32 s77, s91, 0
	s_mov_b32 m0, s17
	v_lshl_add_u64 v[246:247], s[76:77], 0, v[142:143]
	ds_read_b128 v[190:193], v177 offset:32768
	ds_read_b128 v[212:215], v177 offset:33792
	ds_read_b128 v[216:219], v177 offset:34816
	ds_read_b128 v[220:223], v177 offset:35840
	ds_read_b128 v[224:227], v177 offset:36864
	ds_read_b128 v[228:231], v177 offset:37888
	ds_read_b128 v[232:235], v177 offset:38912
	ds_read_b128 v[236:239], v177 offset:39936
	global_load_lds_dwordx4 v[246:247], off
	v_lshl_add_u64 v[246:247], s[76:77], 0, v[146:147]
	s_mov_b32 m0, s18
	s_nop 0
	global_load_lds_dwordx4 v[246:247], off
	s_waitcnt vmcnt(8)
	s_waitcnt lgkmcnt(0)
	s_barrier
	s_setprio 1
	s_waitcnt lgkmcnt(0)
	v_mfma_f32_16x16x32_bf16 v[134:137], v[60:63], v[190:193], v[134:137]
	v_mfma_f32_16x16x32_bf16 v[126:129], v[138:141], v[190:193], v[126:129]
	v_mfma_f32_16x16x32_bf16 v[110:113], v[138:141], v[216:219], v[110:113]
	v_mfma_f32_16x16x32_bf16 v[118:121], v[60:63], v[216:219], v[118:121]
	v_mfma_f32_16x16x32_bf16 v[102:105], v[60:63], v[224:227], v[102:105]
	v_mfma_f32_16x16x32_bf16 v[94:97], v[138:141], v[224:227], v[94:97]
	v_mfma_f32_16x16x32_bf16 v[76:79], v[138:141], v[232:235], v[76:79]
	v_mfma_f32_16x16x32_bf16 v[86:89], v[60:63], v[232:235], v[86:89]
	v_mfma_f32_16x16x32_bf16 v[134:137], v[64:67], v[212:215], v[134:137]
	v_mfma_f32_16x16x32_bf16 v[126:129], v[154:157], v[212:215], v[126:129]
	v_mfma_f32_16x16x32_bf16 v[110:113], v[154:157], v[220:223], v[110:113]
	v_mfma_f32_16x16x32_bf16 v[118:121], v[64:67], v[220:223], v[118:121]
	v_mfma_f32_16x16x32_bf16 v[102:105], v[64:67], v[228:231], v[102:105]
	v_mfma_f32_16x16x32_bf16 v[94:97], v[154:157], v[228:231], v[94:97]
	v_mfma_f32_16x16x32_bf16 v[76:79], v[154:157], v[236:239], v[76:79]
	v_mfma_f32_16x16x32_bf16 v[86:89], v[64:67], v[236:239], v[86:89]
	v_mfma_f32_16x16x32_bf16 v[130:133], v[158:161], v[190:193], v[130:133]
	v_mfma_f32_16x16x32_bf16 v[122:125], v[182:185], v[190:193], v[122:125]
	v_mfma_f32_16x16x32_bf16 v[106:109], v[182:185], v[216:219], v[106:109]
	v_mfma_f32_16x16x32_bf16 v[114:117], v[158:161], v[216:219], v[114:117]
	v_mfma_f32_16x16x32_bf16 v[98:101], v[158:161], v[224:227], v[98:101]
	v_mfma_f32_16x16x32_bf16 v[90:93], v[182:185], v[224:227], v[90:93]
	v_mfma_f32_16x16x32_bf16 v[72:75], v[182:185], v[232:235], v[72:75]
	v_mfma_f32_16x16x32_bf16 v[82:85], v[158:161], v[232:235], v[82:85]
	v_mfma_f32_16x16x32_bf16 v[130:133], v[178:181], v[212:215], v[130:133]
	v_mfma_f32_16x16x32_bf16 v[122:125], v[186:189], v[212:215], v[122:125]
	v_mfma_f32_16x16x32_bf16 v[106:109], v[186:189], v[220:223], v[106:109]
	v_mfma_f32_16x16x32_bf16 v[114:117], v[178:181], v[220:223], v[114:117]
	v_mfma_f32_16x16x32_bf16 v[98:101], v[178:181], v[228:231], v[98:101]
	v_mfma_f32_16x16x32_bf16 v[90:93], v[186:189], v[228:231], v[90:93]
	v_mfma_f32_16x16x32_bf16 v[72:75], v[186:189], v[236:239], v[72:75]
	v_mfma_f32_16x16x32_bf16 v[82:85], v[178:181], v[236:239], v[82:85]
	s_setprio 0
	s_barrier
; #define PG8_STAGE(bufoff, gbase, voff) do { _Pragma("unroll") for (int _i = 0; _i < 2; ++_i) \
;         __builtin_amdgcn_global_load_lds((const unsigned*)((const char*)(gbase) + (voff)[_i]), (PG8_LAS unsigned*)(lds + (bufoff) + ldsw + _i * 8192), 16, 0, 0); } while (0)
; #define PG8_LDA(dst, b, h) do { _Pragma("unroll") for (int m = 0; m < 4; ++m) _Pragma("unroll") for (int k = 0; k < 2; ++k) dst[m][k] = *(const PG8_LAS bf16x8*)(lds + PG8_SA(b, h) + aoff + m * 2048 + k * 1024); } while (0)
; #define PG8_MMA(ai, bj, At, Bt) do { __builtin_amdgcn_s_setprio(1); _Pragma("unroll") for (int m = 0; m < 4; ++m) _Pragma("unroll") for (int n = 0; n < 2; ++n) _Pragma("unroll") for (int k = 0; k < 2; ++k) \
;         acc[ai][bj][m][n] = __builtin_amdgcn_mfma_f32_16x16x32_bf16(Bt[n][k], At[m][k], acc[ai][bj][m][n], 0, 0, 0); __builtin_amdgcn_s_setprio(0); } while (0)
; #define PG8_WAIT_V(n) asm volatile("s_waitcnt vmcnt(" #n ")" ::: "memory")
; #define PG8_WAIT_L(n) asm volatile("s_waitcnt lgkmcnt(" #n ")" ::: "memory")
; #define PG8_BAR __builtin_amdgcn_s_barrier()
; #define PG8_SCHED __builtin_amdgcn_sched_barrier(0)
; template <class Epi, class Sched, bool ALIGN_EPI = false, bool SP2 = false>
; __device__ __forceinline__ void gemm_phase(PG8_LAS unsigned char* lds, const Gemm g, const Sched& S, const Epi& E) {
;     ...
;         for (int t = 0; t < nt; t += 2) {
;     ...
;             PG8_LDA(At, 1, 1); PG8_STAGE(PG8_SB(1, 0), b3, voffB); PG8_STAGE(PG8_SB(1, 1), b3 + hstep, voffB); PG8_STAGE(PG8_SA(1, 0), a3, voffA);
;             PG8_WAIT_V(8); PG8_WAIT_L(0); PG8_BAR; PG8_MMA(1, 0, At, B0); PG8_MMA(1, 1, At, B1); PG8_BAR; PG8_SCHED;
	s_add_i32 s76, s80, s13
	v_lshl_add_u64 v[194:195], v[194:195], 0, s[0:1]
	s_mov_b32 m0, s76
	ds_read_b128 v[190:193], v177 offset:49152
	ds_read_b128 v[212:215], v177 offset:50176
	ds_read_b128 v[216:219], v177 offset:51200
	ds_read_b128 v[220:223], v177 offset:52224
	ds_read_b128 v[224:227], v177 offset:53248
	ds_read_b128 v[228:231], v177 offset:54272
	ds_read_b128 v[232:235], v177 offset:55296
	ds_read_b128 v[236:239], v177 offset:56320
	global_load_lds_dwordx4 v[194:195], off
	s_add_i32 m0, s76, 0x2000
	s_add_u32 s76, s88, 0x40080
	v_lshl_add_u64 v[194:195], v[240:241], 0, s[0:1]
	s_addc_u32 s77, s89, 0
	s_add_i32 s80, s81, s13
	global_load_lds_dwordx4 v[194:195], off
	v_lshl_add_u64 v[194:195], s[76:77], 0, v[144:145]
	s_mov_b32 m0, s80
	s_nop 0
	global_load_lds_dwordx4 v[194:195], off
	v_lshl_add_u64 v[194:195], s[76:77], 0, v[148:149]
	s_add_i32 m0, s80, 0x2000
	s_nop 0
	global_load_lds_dwordx4 v[194:195], off
	v_lshl_add_u64 v[194:195], v[242:243], 0, s[0:1]
	s_mov_b32 m0, s21
	s_nop 0
	global_load_lds_dwordx4 v[194:195], off
	v_lshl_add_u64 v[194:195], v[244:245], 0, s[0:1]
	s_mov_b32 m0, s33
	s_nop 0
	global_load_lds_dwordx4 v[194:195], off
	s_waitcnt vmcnt(8)
	s_waitcnt lgkmcnt(0)
	s_barrier
	s_setprio 1
	s_waitcnt lgkmcnt(0)
	v_mfma_f32_16x16x32_bf16 v[68:71], v[60:63], v[190:193], v[68:71]
	v_mfma_f32_16x16x32_bf16 v[56:59], v[138:141], v[190:193], v[56:59]
	v_mfma_f32_16x16x32_bf16 v[36:39], v[138:141], v[216:219], v[36:39]
	v_mfma_f32_16x16x32_bf16 v[44:47], v[60:63], v[216:219], v[44:47]
	v_mfma_f32_16x16x32_bf16 v[28:31], v[60:63], v[224:227], v[28:31]
	v_mfma_f32_16x16x32_bf16 v[20:23], v[138:141], v[224:227], v[20:23]
	v_mfma_f32_16x16x32_bf16 v[4:7], v[138:141], v[232:235], v[4:7]
	v_mfma_f32_16x16x32_bf16 v[12:15], v[60:63], v[232:235], v[12:15]
	v_mfma_f32_16x16x32_bf16 v[68:71], v[64:67], v[212:215], v[68:71]
	v_mfma_f32_16x16x32_bf16 v[56:59], v[154:157], v[212:215], v[56:59]
	v_mfma_f32_16x16x32_bf16 v[36:39], v[154:157], v[220:223], v[36:39]
	v_mfma_f32_16x16x32_bf16 v[44:47], v[64:67], v[220:223], v[44:47]
	v_mfma_f32_16x16x32_bf16 v[28:31], v[64:67], v[228:231], v[28:31]
	v_mfma_f32_16x16x32_bf16 v[20:23], v[154:157], v[228:231], v[20:23]
	v_mfma_f32_16x16x32_bf16 v[4:7], v[154:157], v[236:239], v[4:7]
	v_mfma_f32_16x16x32_bf16 v[12:15], v[64:67], v[236:239], v[12:15]
	v_mfma_f32_16x16x32_bf16 v[48:51], v[158:161], v[190:193], v[48:51]
	v_mfma_f32_16x16x32_bf16 v[64:67], v[178:181], v[212:215], v[48:51]
	v_mfma_f32_16x16x32_bf16 v[48:51], v[182:185], v[190:193], v[52:55]
	v_mfma_f32_16x16x32_bf16 v[40:43], v[158:161], v[216:219], v[40:43]
	v_mfma_f32_16x16x32_bf16 v[32:35], v[182:185], v[216:219], v[32:35]
	v_mfma_f32_16x16x32_bf16 v[24:27], v[158:161], v[224:227], v[24:27]
	v_mfma_f32_16x16x32_bf16 v[16:19], v[182:185], v[224:227], v[16:19]
	v_mfma_f32_16x16x32_bf16 v[8:11], v[158:161], v[232:235], v[8:11]
	v_mfma_f32_16x16x32_bf16 v[0:3], v[182:185], v[232:235], v[0:3]
	v_mfma_f32_16x16x32_bf16 v[52:55], v[186:189], v[212:215], v[48:51]
	v_mfma_f32_16x16x32_bf16 v[40:43], v[178:181], v[220:223], v[40:43]
	v_mfma_f32_16x16x32_bf16 v[32:35], v[186:189], v[220:223], v[32:35]
	v_mfma_f32_16x16x32_bf16 v[24:27], v[178:181], v[228:231], v[24:27]
	v_mfma_f32_16x16x32_bf16 v[16:19], v[186:189], v[228:231], v[16:19]
	v_mfma_f32_16x16x32_bf16 v[0:3], v[186:189], v[236:239], v[0:3]
	v_mfma_f32_16x16x32_bf16 v[8:11], v[178:181], v[236:239], v[8:11]
	s_setprio 0
	s_barrier
	s_add_i32 s75, s75, 2
	s_add_u32 s86, s86, 0x100
	s_addc_u32 s87, s87, 0
	s_add_u32 s69, s69, 0x100
	s_addc_u32 s71, s71, 0
	s_cmp_gt_u32 s75, 13
	s_cbranch_scc1 .Lpeel_done_2

; #define PG8_BAR __builtin_amdgcn_s_barrier()
; template <class Epi, class Sched, bool ALIGN_EPI = false, bool SP2 = false>
; __device__ __forceinline__ void gemm_phase(PG8_LAS unsigned char* lds, const Gemm g, const Sched& S, const Epi& E) {
;     ...
;         if constexpr (ALIGN_EPI) { if (wr == 0) PG8_BAR; }
.Lpeel_done_2:
	s_and_b64 vcc, exec, s[30:31]
	s_cbranch_vccz .LBB0_239
	s_barrier

; #define PG8_STAGE(bufoff, gbase, voff) do { _Pragma("unroll") for (int _i = 0; _i < 2; ++_i) \
;         __builtin_amdgcn_global_load_lds((const unsigned*)((const char*)(gbase) + (voff)[_i]), (PG8_LAS unsigned*)(lds + (bufoff) + ldsw + _i * 8192), 16, 0, 0); } while (0)
; #define PG8_LDA(dst, b, h) do { _Pragma("unroll") for (int m = 0; m < 4; ++m) _Pragma("unroll") for (int k = 0; k < 2; ++k) dst[m][k] = *(const PG8_LAS bf16x8*)(lds + PG8_SA(b, h) + aoff + m * 2048 + k * 1024); } while (0)
; #define PG8_LDB(dst, b, h) do { _Pragma("unroll") for (int n = 0; n < 2; ++n) _Pragma("unroll") for (int k = 0; k < 2; ++k) dst[n][k] = *(const PG8_LAS bf16x8*)(lds + PG8_SB(b, h) + boff + n * 2048 + k * 1024); } while (0)
; #define PG8_WAIT_V(n) asm volatile("s_waitcnt vmcnt(" #n ")" ::: "memory")
; #define PG8_WAIT_L(n) asm volatile("s_waitcnt lgkmcnt(" #n ")" ::: "memory")
; #define PG8_BAR __builtin_amdgcn_s_barrier()
; template <class Epi, class Sched, bool ALIGN_EPI = false, bool SP2 = false>
; __device__ __forceinline__ void gemm_phase(PG8_LAS unsigned char* lds, const Gemm g, const Sched& S, const Epi& E) {
;     ...
;         const bool has_next = S.next(ui + 1, nxt);
;         const char* nA = has_next ? (const char*)g.A + (size_t)nxt.pm * tstep + (size_t)nxt.kt0 * kstep : cA; const char* nB = has_next ? (const char*)g.Bt + (size_t)nxt.pn * tstep + (size_t)nxt.kt0 * kstep : cB;
;         const int nt = cur.nt;
;         for (int t = 0; t < nt; t += 2) {
;             const bool last = (t == nt - 2);
;             const char* a1 = cA + (size_t)(t + 1) * kstep;
;             const char* a2 = last ? nA : cA + (size_t)(t + 2) * kstep; const char* b2 = last ? nB : cB + (size_t)(t + 2) * kstep;
;             const char* a3 = a2 + kstep; const char* b3 = b2 + kstep;
;             if (last && has_next) S.a_ready(nxt);
;             if constexpr (SP2) {
;             PG8_LDB(B0, 0, 0); PG8_LDB(B1, 0, 1); PG8_SCHED; PG8_LDA(At, 0, 0); PG8_STAGE(PG8_SA(1, 1), a1 + hstep, voffA);
;             PG8_WAIT_V(8); PG8_WAIT_L(0); PG8_BAR; PG8_MMA(0, 0, At, B0); PG8_MMA(0, 1, At, B1); PG8_BAR; PG8_SCHED;
;             PG8_LDA(At, 0, 1); PG8_STAGE(PG8_SB(0, 0), b2, voffB); PG8_STAGE(PG8_SB(0, 1), b2 + hstep, voffB); PG8_STAGE(PG8_SA(0, 0), a2, voffA);
;             PG8_WAIT_V(8); PG8_WAIT_L(0); PG8_BAR; PG8_MMA(1, 0, At, B0); PG8_MMA(1, 1, At, B1); PG8_BAR; PG8_SCHED;
.LBB0_315:
	s_ashr_i32 s31, s30, 31
	s_lshl_b64 s[8:9], s[30:31], 19
	s_add_u32 s74, s68, s8
	s_addc_u32 s75, s69, s9
	s_and_b64 s[8:9], s[36:37], exec
	s_cselect_b32 s3, s75, s41
	s_cselect_b32 s8, s74, s40
	s_ashr_i32 s87, s86, 31
	s_lshl_b64 s[10:11], s[86:87], 19
	v_readlane_b32 s9, v252, 31
	s_add_u32 s88, s9, s10
	v_readlane_b32 s9, v252, 32
	s_addc_u32 s89, s9, s11
	s_and_b64 s[10:11], s[36:37], exec
	s_cselect_b32 s9, s89, s43
	s_cselect_b32 s10, s88, s42
	s_add_u32 s40, s40, 0x40080
	s_addc_u32 s41, s41, 0
	s_add_u32 s11, s42, 0x100
	s_addc_u32 s12, s43, 0
	s_mov_b32 s13, -2
	s_waitcnt vmcnt(0)
	s_add_u32 s14, s40, 0xfffc0080
	s_addc_u32 s15, s41, -1
	s_add_i32 s16, 0, 0x10000
	s_cmp_eq_u32 s13, 12
	s_cselect_b32 s71, s3, s15
	s_cselect_b32 s70, s8, s14
	s_cselect_b32 s43, s9, s12
	s_cselect_b32 s42, s10, s11
	s_add_i32 s17, 0, 0x14000
	s_waitcnt lgkmcnt(0)
	v_add_u32_e32 v44, s16, v214
	v_add_u32_e32 v102, s17, v214
	ds_read_b128 v[32:35], v44
	ds_read_b128 v[36:39], v44 offset:1024
	ds_read_b128 v[40:43], v44 offset:2048
	ds_read_b128 v[44:47], v44 offset:3072
	ds_read_b128 v[90:93], v102
	ds_read_b128 v[94:97], v102 offset:1024
	ds_read_b128 v[98:101], v102 offset:2048
	ds_read_b128 v[102:105], v102 offset:3072
	v_lshl_add_u64 v[194:195], s[40:41], 0, v[178:179]
	s_add_i32 m0, s97, 0xc000
	ds_read_b128 v[182:185], v215
	ds_read_b128 v[186:189], v215 offset:1024
	ds_read_b128 v[190:193], v215 offset:2048
	ds_read_b128 v[216:219], v215 offset:3072
	ds_read_b128 v[220:223], v215 offset:4096
	ds_read_b128 v[224:227], v215 offset:5120
	ds_read_b128 v[228:231], v215 offset:6144
	ds_read_b128 v[232:235], v215 offset:7168
	global_load_lds_dwordx4 v[194:195], off
	v_lshl_add_u64 v[194:195], s[40:41], 0, v[180:181]
	s_add_i32 m0, s97, 0xe000
	s_nop 0
	global_load_lds_dwordx4 v[194:195], off
	s_waitcnt vmcnt(8)
	s_waitcnt lgkmcnt(0)
	s_barrier
	s_setprio 1
	s_waitcnt lgkmcnt(0)
	v_mfma_f32_16x16x32_bf16 v[158:161], v[32:35], v[182:185], 0
	v_mfma_f32_16x16x32_bf16 v[154:157], v[40:43], v[182:185], 0
	v_mfma_f32_16x16x32_bf16 v[138:141], v[40:43], v[190:193], 0
	v_mfma_f32_16x16x32_bf16 v[142:145], v[32:35], v[190:193], 0
	v_mfma_f32_16x16x32_bf16 v[126:129], v[32:35], v[220:223], 0
	v_mfma_f32_16x16x32_bf16 v[122:125], v[40:43], v[220:223], 0
	v_mfma_f32_16x16x32_bf16 v[106:109], v[40:43], v[228:231], 0
	v_mfma_f32_16x16x32_bf16 v[110:113], v[32:35], v[228:231], 0
	v_mfma_f32_16x16x32_bf16 v[158:161], v[36:39], v[186:189], v[158:161]
	v_mfma_f32_16x16x32_bf16 v[154:157], v[44:47], v[186:189], v[154:157]
	v_mfma_f32_16x16x32_bf16 v[138:141], v[44:47], v[216:219], v[138:141]
	v_mfma_f32_16x16x32_bf16 v[142:145], v[36:39], v[216:219], v[142:145]
	v_mfma_f32_16x16x32_bf16 v[126:129], v[36:39], v[224:227], v[126:129]
	v_mfma_f32_16x16x32_bf16 v[122:125], v[44:47], v[224:227], v[122:125]
	v_mfma_f32_16x16x32_bf16 v[106:109], v[44:47], v[232:235], v[106:109]
	v_mfma_f32_16x16x32_bf16 v[110:113], v[36:39], v[232:235], v[110:113]
	v_mfma_f32_16x16x32_bf16 v[150:153], v[90:93], v[182:185], 0
	v_mfma_f32_16x16x32_bf16 v[146:149], v[98:101], v[182:185], 0
	v_mfma_f32_16x16x32_bf16 v[130:133], v[98:101], v[190:193], 0
	v_mfma_f32_16x16x32_bf16 v[134:137], v[90:93], v[190:193], 0
	v_mfma_f32_16x16x32_bf16 v[118:121], v[90:93], v[220:223], 0
	v_mfma_f32_16x16x32_bf16 v[114:117], v[98:101], v[220:223], 0
	v_mfma_f32_16x16x32_bf16 v[82:85], v[98:101], v[228:231], 0
	v_mfma_f32_16x16x32_bf16 v[86:89], v[90:93], v[228:231], 0
	v_mfma_f32_16x16x32_bf16 v[150:153], v[94:97], v[186:189], v[150:153]
	v_mfma_f32_16x16x32_bf16 v[146:149], v[102:105], v[186:189], v[146:149]
	v_mfma_f32_16x16x32_bf16 v[130:133], v[102:105], v[216:219], v[130:133]
	v_mfma_f32_16x16x32_bf16 v[134:137], v[94:97], v[216:219], v[134:137]
	v_mfma_f32_16x16x32_bf16 v[118:121], v[94:97], v[224:227], v[118:121]
	v_mfma_f32_16x16x32_bf16 v[114:117], v[102:105], v[224:227], v[114:117]
	v_mfma_f32_16x16x32_bf16 v[82:85], v[102:105], v[232:235], v[82:85]
	v_mfma_f32_16x16x32_bf16 v[86:89], v[94:97], v[232:235], v[86:89]
	s_setprio 0
	s_barrier
	s_add_i32 s14, s16, s95
	v_lshl_add_u64 v[194:195], s[42:43], 0, v[174:175]
	s_mov_b32 m0, s14
	ds_read_b128 v[182:185], v215 offset:16384
	ds_read_b128 v[186:189], v215 offset:17408
	ds_read_b128 v[190:193], v215 offset:18432
	ds_read_b128 v[216:219], v215 offset:19456
	ds_read_b128 v[220:223], v215 offset:20480
	ds_read_b128 v[224:227], v215 offset:21504
	ds_read_b128 v[228:231], v215 offset:22528
	ds_read_b128 v[232:235], v215 offset:23552
	global_load_lds_dwordx4 v[194:195], off
	s_add_i32 m0, s14, 0x2000
	s_add_u32 s14, s42, 0x40000
	v_lshl_add_u64 v[236:237], s[42:43], 0, v[176:177]
	s_addc_u32 s15, s43, 0
	s_add_i32 s16, s17, s95
	global_load_lds_dwordx4 v[236:237], off
	v_lshl_add_u64 v[238:239], s[14:15], 0, v[174:175]
	s_mov_b32 m0, s16
	v_lshl_add_u64 v[240:241], s[70:71], 0, v[176:177]
	global_load_lds_dwordx4 v[238:239], off
	v_lshl_add_u64 v[238:239], s[14:15], 0, v[176:177]
	s_add_i32 m0, s16, 0x2000
	s_nop 0
	global_load_lds_dwordx4 v[238:239], off
	v_lshl_add_u64 v[238:239], s[70:71], 0, v[174:175]
	s_mov_b32 m0, s97
	s_nop 0
	global_load_lds_dwordx4 v[238:239], off
	s_mov_b32 m0, s98
	s_nop 0
	global_load_lds_dwordx4 v[240:241], off
	s_waitcnt vmcnt(8)
	s_waitcnt lgkmcnt(0)
	s_barrier
; #define PG8_STAGE(bufoff, gbase, voff) do { _Pragma("unroll") for (int _i = 0; _i < 2; ++_i) \
;         __builtin_amdgcn_global_load_lds((const unsigned*)((const char*)(gbase) + (voff)[_i]), (PG8_LAS unsigned*)(lds + (bufoff) + ldsw + _i * 8192), 16, 0, 0); } while (0)
; #define PG8_LDA(dst, b, h) do { _Pragma("unroll") for (int m = 0; m < 4; ++m) _Pragma("unroll") for (int k = 0; k < 2; ++k) dst[m][k] = *(const PG8_LAS bf16x8*)(lds + PG8_SA(b, h) + aoff + m * 2048 + k * 1024); } while (0)
; #define PG8_LDB(dst, b, h) do { _Pragma("unroll") for (int n = 0; n < 2; ++n) _Pragma("unroll") for (int k = 0; k < 2; ++k) dst[n][k] = *(const PG8_LAS bf16x8*)(lds + PG8_SB(b, h) + boff + n * 2048 + k * 1024); } while (0)
; #define PG8_MMA(ai, bj, At, Bt) do { __builtin_amdgcn_s_setprio(1); _Pragma("unroll") for (int m = 0; m < 4; ++m) _Pragma("unroll") for (int n = 0; n < 2; ++n) _Pragma("unroll") for (int k = 0; k < 2; ++k) \
;         acc[ai][bj][m][n] = __builtin_amdgcn_mfma_f32_16x16x32_bf16(Bt[n][k], At[m][k], acc[ai][bj][m][n], 0, 0, 0); __builtin_amdgcn_s_setprio(0); } while (0)
; #define PG8_WAIT_V(n) asm volatile("s_waitcnt vmcnt(" #n ")" ::: "memory")
; #define PG8_WAIT_L(n) asm volatile("s_waitcnt lgkmcnt(" #n ")" ::: "memory")
; #define PG8_BAR __builtin_amdgcn_s_barrier()
; #define PG8_SCHED __builtin_amdgcn_sched_barrier(0)
; template <class Epi, class Sched, bool ALIGN_EPI = false, bool SP2 = false>
; __device__ __forceinline__ void gemm_phase(PG8_LAS unsigned char* lds, const Gemm g, const Sched& S, const Epi& E) {
;     ...
;             PG8_WAIT_V(8); PG8_WAIT_L(0); PG8_BAR; PG8_MMA(1, 0, At, B0); PG8_MMA(1, 1, At, B1); PG8_BAR; PG8_SCHED;
;             PG8_LDB(B0, 1, 0); PG8_LDB(B1, 1, 1); PG8_SCHED; PG8_LDA(At, 1, 0); PG8_STAGE(PG8_SA(0, 1), a2 + hstep, voffA);
;             PG8_WAIT_V(8); PG8_WAIT_L(0); PG8_BAR; PG8_MMA(0, 0, At, B0); PG8_MMA(0, 1, At, B1); PG8_BAR; PG8_SCHED;
	s_setprio 1
	s_waitcnt lgkmcnt(0)
	v_mfma_f32_16x16x32_bf16 v[76:79], v[32:35], v[182:185], 0
	v_mfma_f32_16x16x32_bf16 v[72:75], v[40:43], v[182:185], 0
	v_mfma_f32_16x16x32_bf16 v[56:59], v[40:43], v[190:193], 0
	v_mfma_f32_16x16x32_bf16 v[60:63], v[32:35], v[190:193], 0
	v_mfma_f32_16x16x32_bf16 v[28:31], v[32:35], v[220:223], 0
	v_mfma_f32_16x16x32_bf16 v[24:27], v[40:43], v[220:223], 0
	v_mfma_f32_16x16x32_bf16 v[8:11], v[40:43], v[228:231], 0
	v_mfma_f32_16x16x32_bf16 v[12:15], v[32:35], v[228:231], 0
	v_mfma_f32_16x16x32_bf16 v[76:79], v[36:39], v[186:189], v[76:79]
	v_mfma_f32_16x16x32_bf16 v[72:75], v[44:47], v[186:189], v[72:75]
	v_mfma_f32_16x16x32_bf16 v[56:59], v[44:47], v[216:219], v[56:59]
	v_mfma_f32_16x16x32_bf16 v[60:63], v[36:39], v[216:219], v[60:63]
	v_mfma_f32_16x16x32_bf16 v[28:31], v[36:39], v[224:227], v[28:31]
	v_mfma_f32_16x16x32_bf16 v[24:27], v[44:47], v[224:227], v[24:27]
	v_mfma_f32_16x16x32_bf16 v[8:11], v[44:47], v[232:235], v[8:11]
	v_mfma_f32_16x16x32_bf16 v[12:15], v[36:39], v[232:235], v[12:15]
	v_mfma_f32_16x16x32_bf16 v[20:23], v[90:93], v[220:223], 0
	v_mfma_f32_16x16x32_bf16 v[16:19], v[98:101], v[220:223], 0
	v_mfma_f32_16x16x32_bf16 v[0:3], v[98:101], v[228:231], 0
	v_mfma_f32_16x16x32_bf16 v[4:7], v[90:93], v[228:231], 0
	v_mfma_f32_16x16x32_bf16 v[32:35], v[90:93], v[182:185], 0
	v_mfma_f32_16x16x32_bf16 v[36:39], v[98:101], v[182:185], 0
	v_mfma_f32_16x16x32_bf16 v[44:47], v[98:101], v[190:193], 0
	v_mfma_f32_16x16x32_bf16 v[40:43], v[90:93], v[190:193], 0
	v_mfma_f32_16x16x32_bf16 v[20:23], v[94:97], v[224:227], v[20:23]
	v_mfma_f32_16x16x32_bf16 v[16:19], v[102:105], v[224:227], v[16:19]
	v_mfma_f32_16x16x32_bf16 v[0:3], v[102:105], v[232:235], v[0:3]
	v_mfma_f32_16x16x32_bf16 v[4:7], v[94:97], v[232:235], v[4:7]
	v_mfma_f32_16x16x32_bf16 v[32:35], v[94:97], v[186:189], v[32:35]
	v_mfma_f32_16x16x32_bf16 v[36:39], v[102:105], v[186:189], v[36:39]
	v_mfma_f32_16x16x32_bf16 v[44:47], v[102:105], v[216:219], v[44:47]
	v_mfma_f32_16x16x32_bf16 v[40:43], v[94:97], v[216:219], v[40:43]
	s_setprio 0
	s_barrier
	s_add_i32 s16, 0, 0x18000
	s_add_i32 s17, 0, 0x1c000
	v_add_u32_e32 v68, s16, v214
	v_add_u32_e32 v102, s17, v214
	ds_read_b128 v[48:51], v68
	ds_read_b128 v[52:55], v68 offset:1024
	ds_read_b128 v[64:67], v68 offset:2048
	ds_read_b128 v[68:71], v68 offset:3072
	ds_read_b128 v[90:93], v102
	ds_read_b128 v[94:97], v102 offset:1024
	ds_read_b128 v[98:101], v102 offset:2048
	ds_read_b128 v[102:105], v102 offset:3072
	s_add_u32 s14, s70, 0x40000
	s_addc_u32 s15, s71, 0
	s_mov_b32 m0, s99
	v_lshl_add_u64 v[242:243], s[14:15], 0, v[174:175]
	ds_read_b128 v[182:185], v215 offset:32768
	ds_read_b128 v[186:189], v215 offset:33792
	ds_read_b128 v[190:193], v215 offset:34816
	ds_read_b128 v[216:219], v215 offset:35840
	ds_read_b128 v[220:223], v215 offset:36864
	ds_read_b128 v[224:227], v215 offset:37888
	ds_read_b128 v[228:231], v215 offset:38912
	ds_read_b128 v[232:235], v215 offset:39936
	global_load_lds_dwordx4 v[242:243], off
	v_lshl_add_u64 v[242:243], s[14:15], 0, v[176:177]
	s_mov_b32 m0, s94
	s_nop 0
	global_load_lds_dwordx4 v[242:243], off
	s_waitcnt vmcnt(8)
	s_waitcnt lgkmcnt(0)
	s_barrier
	s_setprio 1
	s_waitcnt lgkmcnt(0)
	v_mfma_f32_16x16x32_bf16 v[158:161], v[48:51], v[182:185], v[158:161]
	v_mfma_f32_16x16x32_bf16 v[154:157], v[64:67], v[182:185], v[154:157]
	v_mfma_f32_16x16x32_bf16 v[138:141], v[64:67], v[190:193], v[138:141]
	v_mfma_f32_16x16x32_bf16 v[142:145], v[48:51], v[190:193], v[142:145]
	v_mfma_f32_16x16x32_bf16 v[126:129], v[48:51], v[220:223], v[126:129]
	v_mfma_f32_16x16x32_bf16 v[122:125], v[64:67], v[220:223], v[122:125]
	v_mfma_f32_16x16x32_bf16 v[106:109], v[64:67], v[228:231], v[106:109]
	v_mfma_f32_16x16x32_bf16 v[110:113], v[48:51], v[228:231], v[110:113]
	v_mfma_f32_16x16x32_bf16 v[158:161], v[52:55], v[186:189], v[158:161]
	v_mfma_f32_16x16x32_bf16 v[154:157], v[68:71], v[186:189], v[154:157]
	v_mfma_f32_16x16x32_bf16 v[138:141], v[68:71], v[216:219], v[138:141]
	v_mfma_f32_16x16x32_bf16 v[142:145], v[52:55], v[216:219], v[142:145]
	v_mfma_f32_16x16x32_bf16 v[126:129], v[52:55], v[224:227], v[126:129]
	v_mfma_f32_16x16x32_bf16 v[122:125], v[68:71], v[224:227], v[122:125]
	v_mfma_f32_16x16x32_bf16 v[106:109], v[68:71], v[232:235], v[106:109]
	v_mfma_f32_16x16x32_bf16 v[110:113], v[52:55], v[232:235], v[110:113]
	v_mfma_f32_16x16x32_bf16 v[150:153], v[90:93], v[182:185], v[150:153]
	v_mfma_f32_16x16x32_bf16 v[146:149], v[98:101], v[182:185], v[146:149]
	v_mfma_f32_16x16x32_bf16 v[130:133], v[98:101], v[190:193], v[130:133]
	v_mfma_f32_16x16x32_bf16 v[134:137], v[90:93], v[190:193], v[134:137]
	v_mfma_f32_16x16x32_bf16 v[118:121], v[90:93], v[220:223], v[118:121]
	v_mfma_f32_16x16x32_bf16 v[114:117], v[98:101], v[220:223], v[114:117]
	v_mfma_f32_16x16x32_bf16 v[82:85], v[98:101], v[228:231], v[82:85]
	v_mfma_f32_16x16x32_bf16 v[86:89], v[90:93], v[228:231], v[86:89]
	v_mfma_f32_16x16x32_bf16 v[150:153], v[94:97], v[186:189], v[150:153]
	v_mfma_f32_16x16x32_bf16 v[146:149], v[102:105], v[186:189], v[146:149]
	v_mfma_f32_16x16x32_bf16 v[130:133], v[102:105], v[216:219], v[130:133]
	v_mfma_f32_16x16x32_bf16 v[134:137], v[94:97], v[216:219], v[134:137]
	v_mfma_f32_16x16x32_bf16 v[118:121], v[94:97], v[224:227], v[118:121]
	v_mfma_f32_16x16x32_bf16 v[114:117], v[102:105], v[224:227], v[114:117]
	v_mfma_f32_16x16x32_bf16 v[82:85], v[102:105], v[232:235], v[82:85]
	v_mfma_f32_16x16x32_bf16 v[86:89], v[94:97], v[232:235], v[86:89]
	s_setprio 0
	s_barrier
; #define PG8_STAGE(bufoff, gbase, voff) do { _Pragma("unroll") for (int _i = 0; _i < 2; ++_i) \
;         __builtin_amdgcn_global_load_lds((const unsigned*)((const char*)(gbase) + (voff)[_i]), (PG8_LAS unsigned*)(lds + (bufoff) + ldsw + _i * 8192), 16, 0, 0); } while (0)
; #define PG8_LDA(dst, b, h) do { _Pragma("unroll") for (int m = 0; m < 4; ++m) _Pragma("unroll") for (int k = 0; k < 2; ++k) dst[m][k] = *(const PG8_LAS bf16x8*)(lds + PG8_SA(b, h) + aoff + m * 2048 + k * 1024); } while (0)
; #define PG8_MMA(ai, bj, At, Bt) do { __builtin_amdgcn_s_setprio(1); _Pragma("unroll") for (int m = 0; m < 4; ++m) _Pragma("unroll") for (int n = 0; n < 2; ++n) _Pragma("unroll") for (int k = 0; k < 2; ++k) \
;         acc[ai][bj][m][n] = __builtin_amdgcn_mfma_f32_16x16x32_bf16(Bt[n][k], At[m][k], acc[ai][bj][m][n], 0, 0, 0); __builtin_amdgcn_s_setprio(0); } while (0)
; #define PG8_WAIT_V(n) asm volatile("s_waitcnt vmcnt(" #n ")" ::: "memory")
; #define PG8_WAIT_L(n) asm volatile("s_waitcnt lgkmcnt(" #n ")" ::: "memory")
; #define PG8_BAR __builtin_amdgcn_s_barrier()
; #define PG8_SCHED __builtin_amdgcn_sched_barrier(0)
; template <class Epi, class Sched, bool ALIGN_EPI = false, bool SP2 = false>
; __device__ __forceinline__ void gemm_phase(PG8_LAS unsigned char* lds, const Gemm g, const Sched& S, const Epi& E) {
;     ...
;             PG8_LDA(At, 1, 1); PG8_STAGE(PG8_SB(1, 0), b3, voffB); PG8_STAGE(PG8_SB(1, 1), b3 + hstep, voffB); PG8_STAGE(PG8_SA(1, 0), a3, voffA);
;             PG8_WAIT_V(8); PG8_WAIT_L(0); PG8_BAR; PG8_MMA(1, 0, At, B0); PG8_MMA(1, 1, At, B1); PG8_BAR; PG8_SCHED;
	s_add_i32 s14, s16, s95
	v_lshl_add_u64 v[194:195], v[194:195], 0, s[0:1]
	s_mov_b32 m0, s14
	ds_read_b128 v[182:185], v215 offset:49152
	ds_read_b128 v[186:189], v215 offset:50176
	ds_read_b128 v[190:193], v215 offset:51200
	ds_read_b128 v[216:219], v215 offset:52224
	ds_read_b128 v[220:223], v215 offset:53248
	ds_read_b128 v[224:227], v215 offset:54272
	ds_read_b128 v[228:231], v215 offset:55296
	ds_read_b128 v[232:235], v215 offset:56320
	global_load_lds_dwordx4 v[194:195], off
	s_add_i32 m0, s14, 0x2000
	s_add_u32 s14, s42, 0x40080
	v_lshl_add_u64 v[194:195], v[236:237], 0, s[0:1]
	s_addc_u32 s15, s43, 0
	s_add_i32 s16, s17, s95
	global_load_lds_dwordx4 v[194:195], off
	v_lshl_add_u64 v[194:195], s[14:15], 0, v[174:175]
	s_mov_b32 m0, s16
	s_nop 0
	global_load_lds_dwordx4 v[194:195], off
	v_lshl_add_u64 v[194:195], s[14:15], 0, v[176:177]
	s_add_i32 m0, s16, 0x2000
	s_nop 0
	global_load_lds_dwordx4 v[194:195], off
	v_lshl_add_u64 v[194:195], v[238:239], 0, s[0:1]
	s_mov_b32 m0, s44
	s_nop 0
	global_load_lds_dwordx4 v[194:195], off
	v_lshl_add_u64 v[194:195], v[240:241], 0, s[0:1]
	s_mov_b32 m0, s45
	s_nop 0
	global_load_lds_dwordx4 v[194:195], off
	s_waitcnt vmcnt(8)
	s_waitcnt lgkmcnt(0)
	s_barrier
	s_setprio 1
	s_waitcnt lgkmcnt(0)
	v_mfma_f32_16x16x32_bf16 v[76:79], v[48:51], v[182:185], v[76:79]
	v_mfma_f32_16x16x32_bf16 v[72:75], v[64:67], v[182:185], v[72:75]
	v_mfma_f32_16x16x32_bf16 v[56:59], v[64:67], v[190:193], v[56:59]
	v_mfma_f32_16x16x32_bf16 v[60:63], v[48:51], v[190:193], v[60:63]
	v_mfma_f32_16x16x32_bf16 v[28:31], v[48:51], v[220:223], v[28:31]
	v_mfma_f32_16x16x32_bf16 v[24:27], v[64:67], v[220:223], v[24:27]
	v_mfma_f32_16x16x32_bf16 v[8:11], v[64:67], v[228:231], v[8:11]
	v_mfma_f32_16x16x32_bf16 v[12:15], v[48:51], v[228:231], v[12:15]
	v_mfma_f32_16x16x32_bf16 v[76:79], v[52:55], v[186:189], v[76:79]
	v_mfma_f32_16x16x32_bf16 v[72:75], v[68:71], v[186:189], v[72:75]
	v_mfma_f32_16x16x32_bf16 v[56:59], v[68:71], v[216:219], v[56:59]
	v_mfma_f32_16x16x32_bf16 v[60:63], v[52:55], v[216:219], v[60:63]
	v_mfma_f32_16x16x32_bf16 v[28:31], v[52:55], v[224:227], v[28:31]
	v_mfma_f32_16x16x32_bf16 v[24:27], v[68:71], v[224:227], v[24:27]
	v_mfma_f32_16x16x32_bf16 v[8:11], v[68:71], v[232:235], v[8:11]
	v_mfma_f32_16x16x32_bf16 v[12:15], v[52:55], v[232:235], v[12:15]
	v_mfma_f32_16x16x32_bf16 v[32:35], v[90:93], v[182:185], v[32:35]
	v_mfma_f32_16x16x32_bf16 v[68:71], v[94:97], v[186:189], v[32:35]
	v_mfma_f32_16x16x32_bf16 v[32:35], v[98:101], v[182:185], v[36:39]
	v_mfma_f32_16x16x32_bf16 v[64:67], v[102:105], v[186:189], v[32:35]
	v_mfma_f32_16x16x32_bf16 v[32:35], v[90:93], v[190:193], v[40:43]
	v_mfma_f32_16x16x32_bf16 v[52:55], v[94:97], v[216:219], v[32:35]
	v_mfma_f32_16x16x32_bf16 v[32:35], v[98:101], v[190:193], v[44:47]
	v_mfma_f32_16x16x32_bf16 v[20:23], v[90:93], v[220:223], v[20:23]
	v_mfma_f32_16x16x32_bf16 v[16:19], v[98:101], v[220:223], v[16:19]
	v_mfma_f32_16x16x32_bf16 v[4:7], v[90:93], v[228:231], v[4:7]
	v_mfma_f32_16x16x32_bf16 v[0:3], v[98:101], v[228:231], v[0:3]
	v_mfma_f32_16x16x32_bf16 v[48:51], v[102:105], v[216:219], v[32:35]
	v_mfma_f32_16x16x32_bf16 v[20:23], v[94:97], v[224:227], v[20:23]
	v_mfma_f32_16x16x32_bf16 v[16:19], v[102:105], v[224:227], v[16:19]
	v_mfma_f32_16x16x32_bf16 v[0:3], v[102:105], v[232:235], v[0:3]
	v_mfma_f32_16x16x32_bf16 v[4:7], v[94:97], v[232:235], v[4:7]
	s_setprio 0
	s_barrier
	s_add_i32 s13, s13, 2
	s_add_u32 s40, s40, 0x100
	s_addc_u32 s41, s41, 0
	s_add_u32 s11, s11, 0x100
	s_addc_u32 s12, s12, 0
	s_cmp_gt_u32 s13, 13
	s_cbranch_scc1 .Lpeel_done_1

; #define PG8_BAR __builtin_amdgcn_s_barrier()
; template <class Epi, class Sched, bool ALIGN_EPI = false, bool SP2 = false>
; __device__ __forceinline__ void gemm_phase(PG8_LAS unsigned char* lds, const Gemm g, const Sched& S, const Epi& E) {
;     ...
;         if constexpr (ALIGN_EPI) { if (wr == 0) PG8_BAR; }
.Lpeel_done_1:
	s_and_b64 vcc, exec, s[22:23]
	s_cbranch_vccz .LBB0_319
	s_barrier

; #define PG8_STAGE(bufoff, gbase, voff) do { _Pragma("unroll") for (int _i = 0; _i < 2; ++_i) \
;         __builtin_amdgcn_global_load_lds((const unsigned*)((const char*)(gbase) + (voff)[_i]), (PG8_LAS unsigned*)(lds + (bufoff) + ldsw + _i * 8192), 16, 0, 0); } while (0)
; #define PG8_LDA(dst, b, h) do { _Pragma("unroll") for (int m = 0; m < 4; ++m) _Pragma("unroll") for (int k = 0; k < 2; ++k) dst[m][k] = *(const PG8_LAS bf16x8*)(lds + PG8_SA(b, h) + aoff + m * 2048 + k * 1024); } while (0)
; #define PG8_LDB(dst, b, h) do { _Pragma("unroll") for (int n = 0; n < 2; ++n) _Pragma("unroll") for (int k = 0; k < 2; ++k) dst[n][k] = *(const PG8_LAS bf16x8*)(lds + PG8_SB(b, h) + boff + n * 2048 + k * 1024); } while (0)
; #define PG8_MMA(ai, bj, At, Bt) do { __builtin_amdgcn_s_setprio(1); _Pragma("unroll") for (int m = 0; m < 4; ++m) _Pragma("unroll") for (int n = 0; n < 2; ++n) _Pragma("unroll") for (int k = 0; k < 2; ++k) \
;         acc[ai][bj][m][n] = __builtin_amdgcn_mfma_f32_16x16x32_bf16(Bt[n][k], At[m][k], acc[ai][bj][m][n], 0, 0, 0); __builtin_amdgcn_s_setprio(0); } while (0)
; #define PG8_WAIT_V(n) asm volatile("s_waitcnt vmcnt(" #n ")" ::: "memory")
; template <class Epi, class Sched, bool ALIGN_EPI = false, bool SP2 = false>
; __device__ __forceinline__ void gemm_phase(PG8_LAS unsigned char* lds, const Gemm g, const Sched& S, const Epi& E) {
;     ...
;         const int nt = cur.nt;
;         for (int t = 0; t < nt; t += 2) {
;             const bool last = (t == nt - 2);
;             const char* a1 = cA + (size_t)(t + 1) * kstep;
;             const char* a2 = last ? nA : cA + (size_t)(t + 2) * kstep; const char* b2 = last ? nB : cB + (size_t)(t + 2) * kstep;
;             const char* a3 = a2 + kstep; const char* b3 = b2 + kstep;
;             if (last && has_next) S.a_ready(nxt);
;             if constexpr (SP2) {
;             PG8_LDB(B0, 0, 0); PG8_LDB(B1, 0, 1); PG8_SCHED; PG8_LDA(At, 0, 0); PG8_STAGE(PG8_SA(1, 1), a1 + hstep, voffA);
;             PG8_WAIT_V(8); PG8_WAIT_L(0); PG8_BAR; PG8_MMA(0, 0, At, B0); PG8_MMA(0, 1, At, B1); PG8_BAR; PG8_SCHED;
;             PG8_LDA(At, 0, 1); PG8_STAGE(PG8_SB(0, 0), b2, voffB); PG8_STAGE(PG8_SB(0, 1), b2 + hstep, voffB); PG8_STAGE(PG8_SA(0, 0), a2, voffA);
;             PG8_WAIT_V(8); PG8_WAIT_L(0); PG8_BAR; PG8_MMA(1, 0, At, B0); PG8_MMA(1, 1, At, B1); PG8_BAR; PG8_SCHED;
.LBB0_646:
	s_add_i32 s24, s44, -2
	s_add_u32 s38, s38, 0x80
	s_addc_u32 s39, s39, 0
	s_add_u32 s41, s42, 0x100
	s_addc_u32 s45, s43, 0
	s_mov_b32 s42, 0
	s_waitcnt lgkmcnt(0)
	s_waitcnt vmcnt(0)
	s_add_i32 s71, s42, 2
	s_add_u32 s81, s38, 0x80
	s_addc_u32 s43, s39, 0
	s_add_i32 s94, 0, 0x10000
	s_cmp_eq_u32 s24, s42
	s_cselect_b32 s43, s27, s43
	s_cselect_b32 s42, s26, s81
	s_cselect_b32 s93, s91, s45
	s_cselect_b32 s92, s90, s41
	s_add_i32 s81, 0, 0x14000
	v_add_u32_e32 v142, s94, v213
	v_add_u32_e32 v151, s81, v213
	ds_read_b128 v[130:133], v142
	ds_read_b128 v[134:137], v142 offset:1024
	ds_read_b128 v[138:141], v142 offset:2048
	ds_read_b128 v[142:145], v142 offset:3072
	ds_read_b128 v[158:161], v151
	ds_read_b128 v[174:177], v151 offset:1024
	ds_read_b128 v[178:181], v151 offset:2048
	ds_read_b128 v[182:185], v151 offset:3072
	v_lshl_add_u64 v[194:195], s[38:39], 0, v[154:155]
	s_add_i32 m0, s17, 0xc000
	ds_read_b128 v[186:189], v214
	ds_read_b128 v[190:193], v214 offset:1024
	ds_read_b128 v[216:219], v214 offset:2048
	ds_read_b128 v[220:223], v214 offset:3072
	ds_read_b128 v[224:227], v214 offset:4096
	ds_read_b128 v[228:231], v214 offset:5120
	ds_read_b128 v[232:235], v214 offset:6144
	ds_read_b128 v[236:239], v214 offset:7168
	global_load_lds_dwordx4 v[194:195], off
	v_lshl_add_u64 v[194:195], s[38:39], 0, v[156:157]
	s_add_i32 m0, s17, 0xe000
	s_nop 0
	global_load_lds_dwordx4 v[194:195], off
	s_waitcnt vmcnt(8)
	s_waitcnt lgkmcnt(0)
	s_barrier
	s_setprio 1
	s_waitcnt lgkmcnt(0)
	v_mfma_f32_16x16x32_bf16 v[126:129], v[130:133], v[186:189], 0
	v_mfma_f32_16x16x32_bf16 v[122:125], v[138:141], v[186:189], 0
	v_mfma_f32_16x16x32_bf16 v[106:109], v[138:141], v[216:219], 0
	v_mfma_f32_16x16x32_bf16 v[110:113], v[130:133], v[216:219], 0
	v_mfma_f32_16x16x32_bf16 v[94:97], v[130:133], v[224:227], 0
	v_mfma_f32_16x16x32_bf16 v[90:93], v[138:141], v[224:227], 0
	v_mfma_f32_16x16x32_bf16 v[72:75], v[138:141], v[232:235], 0
	v_mfma_f32_16x16x32_bf16 v[76:79], v[130:133], v[232:235], 0
	v_mfma_f32_16x16x32_bf16 v[126:129], v[134:137], v[190:193], v[126:129]
	v_mfma_f32_16x16x32_bf16 v[122:125], v[142:145], v[190:193], v[122:125]
	v_mfma_f32_16x16x32_bf16 v[106:109], v[142:145], v[220:223], v[106:109]
	v_mfma_f32_16x16x32_bf16 v[110:113], v[134:137], v[220:223], v[110:113]
	v_mfma_f32_16x16x32_bf16 v[94:97], v[134:137], v[228:231], v[94:97]
	v_mfma_f32_16x16x32_bf16 v[90:93], v[142:145], v[228:231], v[90:93]
	v_mfma_f32_16x16x32_bf16 v[72:75], v[142:145], v[236:239], v[72:75]
	v_mfma_f32_16x16x32_bf16 v[76:79], v[134:137], v[236:239], v[76:79]
	v_mfma_f32_16x16x32_bf16 v[118:121], v[158:161], v[186:189], 0
	v_mfma_f32_16x16x32_bf16 v[114:117], v[178:181], v[186:189], 0
	v_mfma_f32_16x16x32_bf16 v[98:101], v[178:181], v[216:219], 0
	v_mfma_f32_16x16x32_bf16 v[102:105], v[158:161], v[216:219], 0
	v_mfma_f32_16x16x32_bf16 v[86:89], v[158:161], v[224:227], 0
	v_mfma_f32_16x16x32_bf16 v[82:85], v[178:181], v[224:227], 0
	v_mfma_f32_16x16x32_bf16 v[64:67], v[178:181], v[232:235], 0
	v_mfma_f32_16x16x32_bf16 v[68:71], v[158:161], v[232:235], 0
	v_mfma_f32_16x16x32_bf16 v[118:121], v[174:177], v[190:193], v[118:121]
	v_mfma_f32_16x16x32_bf16 v[114:117], v[182:185], v[190:193], v[114:117]
	v_mfma_f32_16x16x32_bf16 v[98:101], v[182:185], v[220:223], v[98:101]
	v_mfma_f32_16x16x32_bf16 v[102:105], v[174:177], v[220:223], v[102:105]
	v_mfma_f32_16x16x32_bf16 v[86:89], v[174:177], v[228:231], v[86:89]
	v_mfma_f32_16x16x32_bf16 v[82:85], v[182:185], v[228:231], v[82:85]
	v_mfma_f32_16x16x32_bf16 v[64:67], v[182:185], v[236:239], v[64:67]
	v_mfma_f32_16x16x32_bf16 v[68:71], v[174:177], v[236:239], v[68:71]
	s_setprio 0
	s_barrier
	s_add_i32 s94, s94, s16
	v_lshl_add_u64 v[194:195], s[92:93], 0, v[146:147]
	s_mov_b32 m0, s94
	ds_read_b128 v[186:189], v214 offset:16384
	ds_read_b128 v[190:193], v214 offset:17408
	ds_read_b128 v[216:219], v214 offset:18432
	ds_read_b128 v[220:223], v214 offset:19456
	ds_read_b128 v[224:227], v214 offset:20480
	ds_read_b128 v[228:231], v214 offset:21504
	ds_read_b128 v[232:235], v214 offset:22528
	ds_read_b128 v[236:239], v214 offset:23552
	global_load_lds_dwordx4 v[194:195], off
	s_add_i32 m0, s94, 0x2000
	v_lshl_add_u64 v[240:241], s[92:93], 0, v[148:149]
	s_add_u32 s92, s92, s30
	s_addc_u32 s93, s93, 0
	s_add_i32 s81, s81, s16
	global_load_lds_dwordx4 v[240:241], off
	v_lshl_add_u64 v[242:243], s[92:93], 0, v[146:147]
	s_mov_b32 m0, s81
	v_lshl_add_u64 v[244:245], s[92:93], 0, v[148:149]
	global_load_lds_dwordx4 v[242:243], off
	s_add_i32 m0, s81, 0x2000
	v_lshl_add_u64 v[246:247], s[42:43], 0, v[146:147]
	global_load_lds_dwordx4 v[244:245], off
	s_mov_b32 m0, s17
	v_lshl_add_u64 v[248:249], s[42:43], 0, v[148:149]
	global_load_lds_dwordx4 v[246:247], off
	s_mov_b32 m0, s18
	s_nop 0
	global_load_lds_dwordx4 v[248:249], off
	s_waitcnt vmcnt(8)
	s_waitcnt lgkmcnt(0)
	s_barrier
; #define PG8_STAGE(bufoff, gbase, voff) do { _Pragma("unroll") for (int _i = 0; _i < 2; ++_i) \
;         __builtin_amdgcn_global_load_lds((const unsigned*)((const char*)(gbase) + (voff)[_i]), (PG8_LAS unsigned*)(lds + (bufoff) + ldsw + _i * 8192), 16, 0, 0); } while (0)
; #define PG8_LDA(dst, b, h) do { _Pragma("unroll") for (int m = 0; m < 4; ++m) _Pragma("unroll") for (int k = 0; k < 2; ++k) dst[m][k] = *(const PG8_LAS bf16x8*)(lds + PG8_SA(b, h) + aoff + m * 2048 + k * 1024); } while (0)
; #define PG8_LDB(dst, b, h) do { _Pragma("unroll") for (int n = 0; n < 2; ++n) _Pragma("unroll") for (int k = 0; k < 2; ++k) dst[n][k] = *(const PG8_LAS bf16x8*)(lds + PG8_SB(b, h) + boff + n * 2048 + k * 1024); } while (0)
; #define PG8_MMA(ai, bj, At, Bt) do { __builtin_amdgcn_s_setprio(1); _Pragma("unroll") for (int m = 0; m < 4; ++m) _Pragma("unroll") for (int n = 0; n < 2; ++n) _Pragma("unroll") for (int k = 0; k < 2; ++k) \
;         acc[ai][bj][m][n] = __builtin_amdgcn_mfma_f32_16x16x32_bf16(Bt[n][k], At[m][k], acc[ai][bj][m][n], 0, 0, 0); __builtin_amdgcn_s_setprio(0); } while (0)
; #define PG8_WAIT_V(n) asm volatile("s_waitcnt vmcnt(" #n ")" ::: "memory")
; #define PG8_WAIT_L(n) asm volatile("s_waitcnt lgkmcnt(" #n ")" ::: "memory")
; #define PG8_BAR __builtin_amdgcn_s_barrier()
; #define PG8_SCHED __builtin_amdgcn_sched_barrier(0)
; template <class Epi, class Sched, bool ALIGN_EPI = false, bool SP2 = false>
; __device__ __forceinline__ void gemm_phase(PG8_LAS unsigned char* lds, const Gemm g, const Sched& S, const Epi& E) {
;     ...
;             PG8_WAIT_V(8); PG8_WAIT_L(0); PG8_BAR; PG8_MMA(1, 0, At, B0); PG8_MMA(1, 1, At, B1); PG8_BAR; PG8_SCHED;
;             PG8_LDB(B0, 1, 0); PG8_LDB(B1, 1, 1); PG8_SCHED; PG8_LDA(At, 1, 0); PG8_STAGE(PG8_SA(0, 1), a2 + hstep, voffA);
;             PG8_WAIT_V(8); PG8_WAIT_L(0); PG8_BAR; PG8_MMA(0, 0, At, B0); PG8_MMA(0, 1, At, B1); PG8_BAR; PG8_SCHED;
	s_setprio 1
	s_waitcnt lgkmcnt(0)
	v_mfma_f32_16x16x32_bf16 v[60:63], v[130:133], v[186:189], 0
	v_mfma_f32_16x16x32_bf16 v[56:59], v[138:141], v[186:189], 0
	v_mfma_f32_16x16x32_bf16 v[40:43], v[138:141], v[216:219], 0
	v_mfma_f32_16x16x32_bf16 v[44:47], v[130:133], v[216:219], 0
	v_mfma_f32_16x16x32_bf16 v[28:31], v[130:133], v[224:227], 0
	v_mfma_f32_16x16x32_bf16 v[24:27], v[138:141], v[224:227], 0
	v_mfma_f32_16x16x32_bf16 v[8:11], v[138:141], v[232:235], 0
	v_mfma_f32_16x16x32_bf16 v[12:15], v[130:133], v[232:235], 0
	v_mfma_f32_16x16x32_bf16 v[60:63], v[134:137], v[190:193], v[60:63]
	v_mfma_f32_16x16x32_bf16 v[56:59], v[142:145], v[190:193], v[56:59]
	v_mfma_f32_16x16x32_bf16 v[40:43], v[142:145], v[220:223], v[40:43]
	v_mfma_f32_16x16x32_bf16 v[44:47], v[134:137], v[220:223], v[44:47]
	v_mfma_f32_16x16x32_bf16 v[28:31], v[134:137], v[228:231], v[28:31]
	v_mfma_f32_16x16x32_bf16 v[24:27], v[142:145], v[228:231], v[24:27]
	v_mfma_f32_16x16x32_bf16 v[8:11], v[142:145], v[236:239], v[8:11]
	v_mfma_f32_16x16x32_bf16 v[12:15], v[134:137], v[236:239], v[12:15]
	v_mfma_f32_16x16x32_bf16 v[52:55], v[158:161], v[186:189], 0
	v_mfma_f32_16x16x32_bf16 v[48:51], v[178:181], v[186:189], 0
	v_mfma_f32_16x16x32_bf16 v[32:35], v[178:181], v[216:219], 0
	v_mfma_f32_16x16x32_bf16 v[36:39], v[158:161], v[216:219], 0
	v_mfma_f32_16x16x32_bf16 v[20:23], v[158:161], v[224:227], 0
	v_mfma_f32_16x16x32_bf16 v[16:19], v[178:181], v[224:227], 0
	v_mfma_f32_16x16x32_bf16 v[0:3], v[178:181], v[232:235], 0
	v_mfma_f32_16x16x32_bf16 v[4:7], v[158:161], v[232:235], 0
	v_mfma_f32_16x16x32_bf16 v[52:55], v[174:177], v[190:193], v[52:55]
	v_mfma_f32_16x16x32_bf16 v[48:51], v[182:185], v[190:193], v[48:51]
	v_mfma_f32_16x16x32_bf16 v[32:35], v[182:185], v[220:223], v[32:35]
	v_mfma_f32_16x16x32_bf16 v[36:39], v[174:177], v[220:223], v[36:39]
	v_mfma_f32_16x16x32_bf16 v[20:23], v[174:177], v[228:231], v[20:23]
	v_mfma_f32_16x16x32_bf16 v[16:19], v[182:185], v[228:231], v[16:19]
	v_mfma_f32_16x16x32_bf16 v[0:3], v[182:185], v[236:239], v[0:3]
	v_mfma_f32_16x16x32_bf16 v[4:7], v[174:177], v[236:239], v[4:7]
	s_setprio 0
	s_barrier
	s_add_i32 s81, 0, 0x18000
	s_add_i32 s92, 0, 0x1c000
	v_add_u32_e32 v142, s81, v213
	v_add_u32_e32 v151, s92, v213
	ds_read_b128 v[130:133], v142
	ds_read_b128 v[134:137], v142 offset:1024
	ds_read_b128 v[138:141], v142 offset:2048
	ds_read_b128 v[142:145], v142 offset:3072
	ds_read_b128 v[158:161], v151
	ds_read_b128 v[174:177], v151 offset:1024
	ds_read_b128 v[178:181], v151 offset:2048
	ds_read_b128 v[182:185], v151 offset:3072
	s_add_u32 s42, s42, s30
	s_addc_u32 s43, s43, 0
	s_mov_b32 m0, s19
	v_lshl_add_u64 v[250:251], s[42:43], 0, v[146:147]
	ds_read_b128 v[186:189], v214 offset:32768
	ds_read_b128 v[190:193], v214 offset:33792
	ds_read_b128 v[216:219], v214 offset:34816
	ds_read_b128 v[220:223], v214 offset:35840
	ds_read_b128 v[224:227], v214 offset:36864
	ds_read_b128 v[228:231], v214 offset:37888
	ds_read_b128 v[232:235], v214 offset:38912
	ds_read_b128 v[236:239], v214 offset:39936
	global_load_lds_dwordx4 v[250:251], off
	v_lshl_add_u64 v[250:251], s[42:43], 0, v[148:149]
	s_mov_b32 m0, s20
	s_nop 0
	global_load_lds_dwordx4 v[250:251], off
	s_waitcnt vmcnt(8)
	s_waitcnt lgkmcnt(0)
	s_barrier
	s_setprio 1
	s_waitcnt lgkmcnt(0)
	v_mfma_f32_16x16x32_bf16 v[126:129], v[130:133], v[186:189], v[126:129]
	v_mfma_f32_16x16x32_bf16 v[122:125], v[138:141], v[186:189], v[122:125]
	v_mfma_f32_16x16x32_bf16 v[106:109], v[138:141], v[216:219], v[106:109]
	v_mfma_f32_16x16x32_bf16 v[110:113], v[130:133], v[216:219], v[110:113]
	v_mfma_f32_16x16x32_bf16 v[94:97], v[130:133], v[224:227], v[94:97]
	v_mfma_f32_16x16x32_bf16 v[90:93], v[138:141], v[224:227], v[90:93]
	v_mfma_f32_16x16x32_bf16 v[72:75], v[138:141], v[232:235], v[72:75]
	v_mfma_f32_16x16x32_bf16 v[76:79], v[130:133], v[232:235], v[76:79]
	v_mfma_f32_16x16x32_bf16 v[126:129], v[134:137], v[190:193], v[126:129]
	v_mfma_f32_16x16x32_bf16 v[122:125], v[142:145], v[190:193], v[122:125]
	v_mfma_f32_16x16x32_bf16 v[106:109], v[142:145], v[220:223], v[106:109]
	v_mfma_f32_16x16x32_bf16 v[110:113], v[134:137], v[220:223], v[110:113]
	v_mfma_f32_16x16x32_bf16 v[94:97], v[134:137], v[228:231], v[94:97]
	v_mfma_f32_16x16x32_bf16 v[90:93], v[142:145], v[228:231], v[90:93]
	v_mfma_f32_16x16x32_bf16 v[72:75], v[142:145], v[236:239], v[72:75]
	v_mfma_f32_16x16x32_bf16 v[76:79], v[134:137], v[236:239], v[76:79]
	v_mfma_f32_16x16x32_bf16 v[118:121], v[158:161], v[186:189], v[118:121]
	v_mfma_f32_16x16x32_bf16 v[114:117], v[178:181], v[186:189], v[114:117]
	v_mfma_f32_16x16x32_bf16 v[98:101], v[178:181], v[216:219], v[98:101]
	v_mfma_f32_16x16x32_bf16 v[102:105], v[158:161], v[216:219], v[102:105]
	v_mfma_f32_16x16x32_bf16 v[86:89], v[158:161], v[224:227], v[86:89]
	v_mfma_f32_16x16x32_bf16 v[82:85], v[178:181], v[224:227], v[82:85]
	v_mfma_f32_16x16x32_bf16 v[64:67], v[178:181], v[232:235], v[64:67]
	v_mfma_f32_16x16x32_bf16 v[68:71], v[158:161], v[232:235], v[68:71]
	v_mfma_f32_16x16x32_bf16 v[118:121], v[174:177], v[190:193], v[118:121]
	v_mfma_f32_16x16x32_bf16 v[114:117], v[182:185], v[190:193], v[114:117]
	v_mfma_f32_16x16x32_bf16 v[98:101], v[182:185], v[220:223], v[98:101]
	v_mfma_f32_16x16x32_bf16 v[102:105], v[174:177], v[220:223], v[102:105]
	v_mfma_f32_16x16x32_bf16 v[86:89], v[174:177], v[228:231], v[86:89]
	v_mfma_f32_16x16x32_bf16 v[82:85], v[182:185], v[228:231], v[82:85]
	v_mfma_f32_16x16x32_bf16 v[64:67], v[182:185], v[236:239], v[64:67]
	v_mfma_f32_16x16x32_bf16 v[68:71], v[174:177], v[236:239], v[68:71]
	s_setprio 0
	s_barrier
; #define PG8_STAGE(bufoff, gbase, voff) do { _Pragma("unroll") for (int _i = 0; _i < 2; ++_i) \
;         __builtin_amdgcn_global_load_lds((const unsigned*)((const char*)(gbase) + (voff)[_i]), (PG8_LAS unsigned*)(lds + (bufoff) + ldsw + _i * 8192), 16, 0, 0); } while (0)
; #define PG8_LDA(dst, b, h) do { _Pragma("unroll") for (int m = 0; m < 4; ++m) _Pragma("unroll") for (int k = 0; k < 2; ++k) dst[m][k] = *(const PG8_LAS bf16x8*)(lds + PG8_SA(b, h) + aoff + m * 2048 + k * 1024); } while (0)
; #define PG8_MMA(ai, bj, At, Bt) do { __builtin_amdgcn_s_setprio(1); _Pragma("unroll") for (int m = 0; m < 4; ++m) _Pragma("unroll") for (int n = 0; n < 2; ++n) _Pragma("unroll") for (int k = 0; k < 2; ++k) \
;         acc[ai][bj][m][n] = __builtin_amdgcn_mfma_f32_16x16x32_bf16(Bt[n][k], At[m][k], acc[ai][bj][m][n], 0, 0, 0); __builtin_amdgcn_s_setprio(0); } while (0)
; #define PG8_WAIT_V(n) asm volatile("s_waitcnt vmcnt(" #n ")" ::: "memory")
; #define PG8_WAIT_L(n) asm volatile("s_waitcnt lgkmcnt(" #n ")" ::: "memory")
; #define PG8_BAR __builtin_amdgcn_s_barrier()
; #define PG8_SCHED __builtin_amdgcn_sched_barrier(0)
; template <class Epi, class Sched, bool ALIGN_EPI = false, bool SP2 = false>
; __device__ __forceinline__ void gemm_phase(PG8_LAS unsigned char* lds, const Gemm g, const Sched& S, const Epi& E) {
;     ...
;             PG8_LDA(At, 1, 1); PG8_STAGE(PG8_SB(1, 0), b3, voffB); PG8_STAGE(PG8_SB(1, 1), b3 + hstep, voffB); PG8_STAGE(PG8_SA(1, 0), a3, voffA);
;             PG8_WAIT_V(8); PG8_WAIT_L(0); PG8_BAR; PG8_MMA(1, 0, At, B0); PG8_MMA(1, 1, At, B1); PG8_BAR; PG8_SCHED;
	s_add_i32 s42, s81, s16
	v_lshl_add_u64 v[194:195], v[194:195], 0, s[0:1]
	s_mov_b32 m0, s42
	ds_read_b128 v[186:189], v214 offset:49152
	ds_read_b128 v[190:193], v214 offset:50176
	ds_read_b128 v[216:219], v214 offset:51200
	ds_read_b128 v[220:223], v214 offset:52224
	ds_read_b128 v[224:227], v214 offset:53248
	ds_read_b128 v[228:231], v214 offset:54272
	ds_read_b128 v[232:235], v214 offset:55296
	ds_read_b128 v[236:239], v214 offset:56320
	global_load_lds_dwordx4 v[194:195], off
	v_lshl_add_u64 v[194:195], v[240:241], 0, s[0:1]
	s_add_i32 m0, s42, 0x2000
	s_add_i32 s42, s92, s16
	global_load_lds_dwordx4 v[194:195], off
	v_lshl_add_u64 v[194:195], v[242:243], 0, s[0:1]
	s_mov_b32 m0, s42
	s_nop 0
	global_load_lds_dwordx4 v[194:195], off
	v_lshl_add_u64 v[194:195], v[244:245], 0, s[0:1]
	s_add_i32 m0, s42, 0x2000
	s_nop 0
	global_load_lds_dwordx4 v[194:195], off
	v_lshl_add_u64 v[194:195], v[246:247], 0, s[0:1]
	s_mov_b32 m0, s8
	s_nop 0
	global_load_lds_dwordx4 v[194:195], off
	v_lshl_add_u64 v[194:195], v[248:249], 0, s[0:1]
	s_mov_b32 m0, s9
	s_nop 0
	global_load_lds_dwordx4 v[194:195], off
	s_waitcnt vmcnt(8)
	s_waitcnt lgkmcnt(0)
	s_barrier
	s_setprio 1
	s_waitcnt lgkmcnt(0)
	v_mfma_f32_16x16x32_bf16 v[60:63], v[130:133], v[186:189], v[60:63]
	v_mfma_f32_16x16x32_bf16 v[56:59], v[138:141], v[186:189], v[56:59]
	v_mfma_f32_16x16x32_bf16 v[40:43], v[138:141], v[216:219], v[40:43]
	v_mfma_f32_16x16x32_bf16 v[44:47], v[130:133], v[216:219], v[44:47]
	v_mfma_f32_16x16x32_bf16 v[28:31], v[130:133], v[224:227], v[28:31]
	v_mfma_f32_16x16x32_bf16 v[24:27], v[138:141], v[224:227], v[24:27]
	v_mfma_f32_16x16x32_bf16 v[8:11], v[138:141], v[232:235], v[8:11]
	v_mfma_f32_16x16x32_bf16 v[12:15], v[130:133], v[232:235], v[12:15]
	v_mfma_f32_16x16x32_bf16 v[60:63], v[134:137], v[190:193], v[60:63]
	v_mfma_f32_16x16x32_bf16 v[56:59], v[142:145], v[190:193], v[56:59]
	v_mfma_f32_16x16x32_bf16 v[40:43], v[142:145], v[220:223], v[40:43]
	v_mfma_f32_16x16x32_bf16 v[44:47], v[134:137], v[220:223], v[44:47]
	v_mfma_f32_16x16x32_bf16 v[28:31], v[134:137], v[228:231], v[28:31]
	v_mfma_f32_16x16x32_bf16 v[24:27], v[142:145], v[228:231], v[24:27]
	v_mfma_f32_16x16x32_bf16 v[8:11], v[142:145], v[236:239], v[8:11]
	v_mfma_f32_16x16x32_bf16 v[12:15], v[134:137], v[236:239], v[12:15]
	v_mfma_f32_16x16x32_bf16 v[52:55], v[158:161], v[186:189], v[52:55]
	v_mfma_f32_16x16x32_bf16 v[48:51], v[178:181], v[186:189], v[48:51]
	v_mfma_f32_16x16x32_bf16 v[32:35], v[178:181], v[216:219], v[32:35]
	v_mfma_f32_16x16x32_bf16 v[36:39], v[158:161], v[216:219], v[36:39]
	v_mfma_f32_16x16x32_bf16 v[20:23], v[158:161], v[224:227], v[20:23]
	v_mfma_f32_16x16x32_bf16 v[16:19], v[178:181], v[224:227], v[16:19]
	v_mfma_f32_16x16x32_bf16 v[0:3], v[178:181], v[232:235], v[0:3]
	v_mfma_f32_16x16x32_bf16 v[4:7], v[158:161], v[232:235], v[4:7]
	v_mfma_f32_16x16x32_bf16 v[52:55], v[174:177], v[190:193], v[52:55]
	v_mfma_f32_16x16x32_bf16 v[48:51], v[182:185], v[190:193], v[48:51]
	v_mfma_f32_16x16x32_bf16 v[32:35], v[182:185], v[220:223], v[32:35]
	v_mfma_f32_16x16x32_bf16 v[36:39], v[174:177], v[220:223], v[36:39]
	v_mfma_f32_16x16x32_bf16 v[20:23], v[174:177], v[228:231], v[20:23]
	v_mfma_f32_16x16x32_bf16 v[16:19], v[182:185], v[228:231], v[16:19]
	v_mfma_f32_16x16x32_bf16 v[0:3], v[182:185], v[236:239], v[0:3]
	v_mfma_f32_16x16x32_bf16 v[4:7], v[174:177], v[236:239], v[4:7]
	s_setprio 0
	s_barrier
	s_add_u32 s38, s38, 0x100
	s_addc_u32 s39, s39, 0
	s_add_u32 s41, s41, 0x100
	s_addc_u32 s45, s45, 0
	s_cmp_ge_u32 s71, s44
	s_mov_b32 s42, s71
	s_cbranch_scc1 .Lpeel_done_0

; #define PG8_BAR __builtin_amdgcn_s_barrier()
; template <class Epi, class Sched, bool ALIGN_EPI = false, bool SP2 = false>
; __device__ __forceinline__ void gemm_phase(PG8_LAS unsigned char* lds, const Gemm g, const Sched& S, const Epi& E) {
;     ...
;         if constexpr (ALIGN_EPI) { if (wr == 0) PG8_BAR; }
.Lpeel_done_0:
	s_and_b64 vcc, exec, s[88:89]
	s_cbranch_vccz .LBB0_650
	s_barrier
